# priority raise (s_setprio 3) for the wave-0 gate sections of mlstm_a and mlstm_c, reset to 0 after
# baseline (speedup 1.0000x reference)
; __device__ __forceinline__ float logsigmoidf_(float x) { return fminf(x, 0.f) - log1pf(__expf(-fabsf(x))); }
; __device__ __forceinline__ void phase_mlstm_a(const Args& a, unsigned char* lds) {
;     ...
;     for (int item = blockIdx.x; item < 4096; item += gridDim.x) {
;         const int c = item & 127, h = (item >> 7) & 3, b = item >> 9;
;         const size_t r0 = (size_t)b * SEQ + c * 64;
;         if (wave == 0) {
;             const float ig = SM[(r0 + lane) * 16 + 8 + h] + a.in[I_BI][h];
;             const float lf = logsigmoidf_(SM[(r0 + lane) * 16 + 12 + h] + a.in[I_BF][h]);
;             const float bs = wave_incl_sum(lf, lane);
;             const float bl = __shfl(bs, 63);
;             const float wk = bl - bs + ig;
;             const float ml = wave_max(wk);
;             WS_[lane] = __expf(wk - ml);
;             if (lane == 0) { ML[item] = ml; BL[item] = bl; }
;         }
.LBB0_656:
	s_ashr_i32 s16, s14, 9
	s_ashr_i32 s17, s16, 31
	s_lshl_b32 s60, s14, 6
	s_lshl_b64 s[18:19], s[16:17], 13
	s_and_b32 s10, s60, 0x1fc0
	s_bfe_u32 s61, s14, 0x20007
	s_or_b32 s16, s18, s10
	s_mov_b32 s17, s19
	s_lshr_b32 s10, s14, 7
	s_and_b32 s15, s27, 0x1fc0
	s_and_b32 s10, s10, 3
	s_add_u32 s18, s15, s18
	s_addc_u32 s19, 0, s19
	v_lshl_add_u64 v[252:253], s[18:19], 0, v[16:17]
	v_mad_u64_u32 v[250:251], vcc, v252, s42, 0
	v_mad_i32_i24 v253, v253, s42, v251
	v_lshl_or_b32 v252, s10, 8, v250
	v_lshl_add_u64 v[252:253], v[2:3], 0, v[252:253]
	s_lshl_b32 s10, s61, 7
	global_load_dwordx4 v[228:231], v[252:253], off
	s_nop 0
	v_lshl_add_u64 v[252:253], v[252:253], 0, s[12:13]
	global_load_dwordx4 v[232:235], v[252:253], off
	s_nop 0
	v_lshl_add_u64 v[252:253], s[16:17], 0, v[128:129]
	v_lshlrev_b64 v[252:253], 10, v[252:253]
	v_lshl_add_u64 v[252:253], s[70:71], 0, v[252:253]
	v_lshl_add_u64 v[252:253], v[252:253], 0, s[10:11]
	v_lshlrev_b32_e32 v250, 1, v146
	v_mov_b32_e32 v251, v1
	v_lshl_add_u64 v[252:253], v[252:253], 0, v[250:251]
	v_add_co_u32_e32 v252, vcc, 0x3c000000, v252
	s_nop 1
	v_addc_co_u32_e32 v253, vcc, 0, v253, vcc
	global_load_dwordx4 v[236:239], v[252:253], off offset:512
	s_and_saveexec_b64 s[20:21], s[4:5]
	s_cbranch_execz .LBB0_659
	s_setprio 3
	v_mov_b32_e32 v5, s17
	v_or_b32_e32 v4, s16, v156
	v_lshlrev_b64 v[4:5], 6, v[4:5]
	v_lshl_add_u64 v[4:5], s[58:59], 0, v[4:5]
	s_lshl_b32 s10, s61, 2
	v_lshl_add_u64 v[4:5], v[4:5], 0, s[10:11]
	v_mov_b32_e32 v0, s10
	global_load_dword v37, v[4:5], off offset:48
	global_load_dword v39, v0, s[50:51]
	global_load_dword v38, v0, s[48:49]
	s_nop 0
	global_load_dword v4, v[4:5], off offset:32
	s_waitcnt vmcnt(2)
	v_add_f32_e32 v0, v37, v39
	v_mul_f32_e64 v5, |v0|, s29
	v_exp_f32_e32 v5, v5
	v_min_f32_e32 v0, 0, v0
	v_mov_b32_e32 v37, 0
	v_mov_b32_e32 v39, 0
	v_add_f32_e32 v42, 1.0, v5
	v_add_f32_e32 v43, -1.0, v42
	v_frexp_mant_f32_e32 v44, v42
	v_cvt_f64_f32_e32 v[40:41], v42
	v_sub_f32_e32 v45, v43, v42
	v_frexp_exp_i32_f64_e32 v40, v[40:41]
	v_cmp_gt_f32_e32 vcc, s38, v44
	v_sub_f32_e32 v43, v5, v43
	v_add_f32_e32 v41, 1.0, v45
	v_subbrev_co_u32_e32 v40, vcc, 0, v40, vcc
	v_add_f32_e32 v41, v43, v41
	v_sub_u32_e32 v43, 0, v40
	v_cvt_f32_i32_e32 v40, v40
	v_ldexp_f32 v42, v42, v43
	v_ldexp_f32 v41, v41, v43
	v_add_f32_e32 v43, -1.0, v42
	v_add_f32_e32 v44, 1.0, v42
	v_add_f32_e32 v45, 1.0, v43
	v_add_f32_e32 v46, -1.0, v44
	v_sub_f32_e32 v45, v42, v45
	v_sub_f32_e32 v42, v42, v46
	v_mul_f32_e32 v46, 0x3f317218, v40
	v_add_f32_e32 v45, v41, v45
	v_add_f32_e32 v41, v41, v42
	v_fma_f32 v42, v40, s39, -v46
	v_add_f32_e32 v47, v43, v45
	v_add_f32_e32 v48, v44, v41
	v_fmac_f32_e32 v42, 0xb102e308, v40
	v_sub_f32_e32 v40, v47, v43
	v_sub_f32_e32 v43, v48, v44
	v_rcp_f32_e32 v44, v48
	v_add_f32_e32 v49, v46, v42
	v_sub_f32_e32 v41, v41, v43
	v_sub_f32_e32 v43, v49, v46
	v_sub_f32_e32 v42, v42, v43
	v_mul_f32_e32 v43, v47, v44
	v_sub_f32_e32 v40, v45, v40
	v_mul_f32_e32 v45, v48, v43
	v_fma_f32 v46, v43, v48, -v45
	v_fmac_f32_e32 v46, v43, v41
	v_add_f32_e32 v50, v45, v46
	v_sub_f32_e32 v51, v47, v50
	v_sub_f32_e32 v45, v50, v45
	v_sub_f32_e32 v47, v47, v51
	v_sub_f32_e32 v45, v45, v46
	v_sub_f32_e32 v46, v47, v50
	v_add_f32_e32 v40, v40, v46
	v_add_f32_e32 v40, v45, v40
	v_add_f32_e32 v45, v51, v40
	v_mul_f32_e32 v46, v44, v45
	v_sub_f32_e32 v47, v51, v45
	v_mul_f32_e32 v50, v48, v46
	v_add_f32_e32 v40, v40, v47
	v_add_f32_e32 v47, v43, v46
	v_fma_f32 v48, v46, v48, -v50
	v_sub_f32_e32 v43, v47, v43
	v_fmac_f32_e32 v48, v46, v41
	v_sub_f32_e32 v41, v46, v43
	v_add_f32_e32 v43, v50, v48
	v_sub_f32_e32 v46, v43, v50
	v_sub_f32_e32 v50, v45, v43
	v_sub_f32_e32 v45, v45, v50
	v_sub_f32_e32 v43, v45, v43
	v_sub_f32_e32 v46, v46, v48
	v_add_f32_e32 v40, v40, v43
	v_add_f32_e32 v40, v46, v40
	v_add_f32_e32 v40, v50, v40
	v_mul_f32_e32 v40, v44, v40
	v_add_f32_e32 v40, v41, v40
	v_add_f32_e32 v41, v47, v40
	v_mul_f32_e32 v43, v41, v41
	v_fmamk_f32 v46, v43, 0x3e9b6dac, v13
	v_sub_f32_e32 v44, v41, v47
	v_ldexp_f32 v45, v41, 1
	v_mul_f32_e32 v41, v41, v43
	v_fmaak_f32 v43, v43, v46, 0x3f2aaada
	v_mul_f32_e32 v41, v41, v43
	v_add_f32_e32 v43, v45, v41
	v_sub_f32_e32 v40, v40, v44
	v_sub_f32_e32 v44, v43, v45
	v_ldexp_f32 v40, v40, 1
	v_sub_f32_e32 v41, v41, v44
	v_add_f32_e32 v40, v40, v41
	v_add_f32_e32 v41, v43, v40
	v_sub_f32_e32 v43, v41, v43
	v_add_f32_e32 v44, v49, v41
	v_sub_f32_e32 v40, v40, v43
	v_sub_f32_e32 v43, v44, v49
	v_sub_f32_e32 v45, v44, v43
	v_sub_f32_e32 v41, v41, v43
	v_add_f32_e32 v43, v42, v40
	v_sub_f32_e32 v45, v49, v45
	v_sub_f32_e32 v46, v43, v42
	v_add_f32_e32 v41, v41, v45
	v_sub_f32_e32 v45, v43, v46
	v_sub_f32_e32 v40, v40, v46
	v_sub_f32_e32 v42, v42, v45
	v_add_f32_e32 v41, v43, v41
	v_add_f32_e32 v40, v40, v42
	v_add_f32_e32 v42, v44, v41
	v_sub_f32_e32 v43, v42, v44
	v_sub_f32_e32 v41, v41, v43
	v_add_f32_e32 v40, v40, v41
	v_add_f32_e32 v40, v42, v40
	v_cmp_neq_f32_e32 vcc, s40, v5
	s_nop 1
	v_cndmask_b32_e32 v40, v29, v40, vcc
	v_cmp_ngt_f32_e32 vcc, -1.0, v5
	s_nop 1
	v_cndmask_b32_e32 v40, v30, v40, vcc
	v_cmp_neq_f32_e32 vcc, -1.0, v5
	s_nop 1
	v_cndmask_b32_e32 v40, v31, v40, vcc
	v_cmp_lt_f32_e64 vcc, |v5|, s41
	s_nop 1
	v_cndmask_b32_e32 v5, v40, v5, vcc
	v_sub_f32_e32 v0, v0, v5
	v_cmp_lt_i32_e32 vcc, v18, v15
	s_nop 0
	v_add_f32_dpp v0, v0, v0 row_shr:1 row_mask:0xf bank_mask:0xf bound_ctrl:1
	s_nop 1
	v_add_f32_dpp v0, v0, v0 row_shr:2 row_mask:0xf bank_mask:0xf bound_ctrl:1
	s_nop 1
	v_add_f32_dpp v0, v0, v0 row_shr:4 row_mask:0xf bank_mask:0xf bound_ctrl:1
	s_nop 1
	v_add_f32_dpp v0, v0, v0 row_shr:8 row_mask:0xf bank_mask:0xf bound_ctrl:1
	s_nop 1
	v_mov_b32_dpp v37, v0 row_bcast:15 row_mask:0xa bank_mask:0xf
	v_add_f32_e32 v5, v0, v37
	v_cndmask_b32_e32 v37, v14, v18, vcc
	v_lshlrev_b32_e32 v37, 2, v37
	v_mov_b32_dpp v39, v5 row_bcast:31 row_mask:0xc bank_mask:0xf
	s_waitcnt vmcnt(0)
; __device__ __forceinline__ bf16_t f2bf(float f) { return (bf16_t)(cvt_pk_bf16(f, 0.f) & 0xffffu); }
; __device__ __forceinline__ bf16_t f2bf_sw(float f) { const unsigned u = __float_as_uint(f); return (bf16_t)((u + 0x7fffu + ((u >> 16) & 1u)) >> 16); }
; __device__ __forceinline__ void phase_mlstm_a(const Args& a, unsigned char* lds) {
;     ...
;             const float bl = __shfl(bs, 63);
;             const float wk = bl - bs + ig;
;             const float ml = wave_max(wk);
;             WS_[lane] = __expf(wk - ml);
;             if (lane == 0) { ML[item] = ml; BL[item] = bl; }
;         }
;         for (int i = tid; i < 1024; i += 512) { const int s = i >> 4, d0 = (i & 15) * 8; float f[8]; unpack8(*(const u32x4*)(P + (r0 + s) * LDP + C_MV + h * 128 + d0), f);
; #pragma unroll
;             for (int e = 0; e < 8; ++e) VT[(d0 + e) * 72 + s] = f2bf(f[e]); }
;         __syncthreads();
;         { const int s = tid >> 3, d0 = (tid & 7) * 8; float f[8]; unpack8(*(const u32x4*)(QK + (r0 + s) * 512 + 256 + h * 64 + d0), f); const float w = WS_[s];
; #pragma unroll
;             for (int e = 0; e < 8; ++e) KT[(d0 + e) * 72 + s] = f2bf(f[e] * w); }
;         __syncthreads();
;         bf16_t* st = ST + (size_t)item * 8192;
; #pragma unroll
;         for (int nt = 0; nt < 4; ++nt) {
;             const f32x4 acc = mma_lds(VT + wave * 16 * 72, 72, KT + nt * 16 * 72, 72, 64, lane);
; #pragma unroll
;             for (int j = 0; j < 4; ++j) st[(wave * 16 + (lane >> 4) * 4 + j) * 64 + nt * 16 + (lane & 15)] = f2bf_sw(acc[j]);
	v_pk_add_f32 v[4:5], v[4:5], v[38:39]
	ds_bpermute_b32 v0, v35, v5
	v_cmp_lt_i32_e32 vcc, v19, v15
	s_waitcnt lgkmcnt(0)
	v_sub_f32_e32 v5, v0, v5
	v_add_f32_e32 v5, v4, v5
	ds_bpermute_b32 v4, v37, v5
	v_cndmask_b32_e32 v37, v14, v19, vcc
	v_lshlrev_b32_e32 v37, 2, v37
	v_cmp_lt_i32_e32 vcc, v20, v15
	s_waitcnt lgkmcnt(0)
	v_max_f32_e32 v4, v4, v4
	v_max_f32_e32 v4, v5, v4
	ds_bpermute_b32 v37, v37, v4
	v_cndmask_b32_e32 v38, v14, v20, vcc
	v_lshlrev_b32_e32 v38, 2, v38
	v_cmp_lt_i32_e32 vcc, v21, v15
	s_waitcnt lgkmcnt(0)
	v_max_f32_e32 v37, v37, v37
	v_max_f32_e32 v4, v4, v37
	ds_bpermute_b32 v37, v38, v4
	v_cndmask_b32_e32 v38, v14, v21, vcc
	v_lshlrev_b32_e32 v38, 2, v38
	v_cmp_lt_i32_e32 vcc, v22, v15
	s_waitcnt lgkmcnt(0)
	v_max_f32_e32 v37, v37, v37
	v_max_f32_e32 v4, v4, v37
	ds_bpermute_b32 v37, v38, v4
	v_cndmask_b32_e32 v38, v14, v22, vcc
	v_lshlrev_b32_e32 v38, 2, v38
	v_cmp_lt_i32_e32 vcc, v36, v15
	s_waitcnt lgkmcnt(0)
	v_max_f32_e32 v37, v37, v37
	v_max_f32_e32 v4, v4, v37
	ds_bpermute_b32 v37, v38, v4
	v_cndmask_b32_e32 v38, v14, v36, vcc
	s_waitcnt lgkmcnt(0)
	v_max_f32_e32 v37, v37, v37
	v_max_f32_e32 v4, v4, v37
	v_lshlrev_b32_e32 v37, 2, v38
	ds_bpermute_b32 v37, v37, v4
	s_waitcnt lgkmcnt(0)
	v_max_f32_e32 v37, v37, v37
	v_max_f32_e32 v4, v4, v37
	v_sub_f32_e32 v5, v5, v4
	v_mul_f32_e32 v5, 0x3fb8aa3b, v5
	v_exp_f32_e32 v5, v5
	ds_write_b32 v6, v5 offset:27648
	s_and_b64 exec, exec, s[6:7]
	s_cbranch_execz .LBB0_659
	s_ashr_i32 s15, s14, 31
	s_lshl_b64 s[62:63], s[14:15], 2
	s_add_u32 s64, s22, s62
	s_addc_u32 s65, s23, s63
	s_add_u32 s62, s24, s62
	s_addc_u32 s63, s25, s63
	global_store_dword v1, v4, s[64:65]
	global_store_dword v1, v0, s[62:63]
.LBB0_659:
	s_or_b64 exec, exec, s[20:21]
	s_setprio 0
	v_and_b32_e32 v39, 0x78, v162
	v_mad_u32_u24 v39, v39, s26, v12
	s_waitcnt vmcnt(2)
	ds_write_b16 v39, v228
	ds_write_b16_d16_hi v39, v228 offset:144
	ds_write_b16 v39, v229 offset:288
	ds_write_b16_d16_hi v39, v229 offset:432
	ds_write_b16 v39, v230 offset:576
	ds_write_b16_d16_hi v39, v230 offset:720
	ds_write_b16 v39, v231 offset:864
	ds_write_b16_d16_hi v39, v231 offset:1008
	s_waitcnt vmcnt(1)
	ds_write_b16 v39, v232 offset:64
	ds_write_b16_d16_hi v39, v232 offset:208
	ds_write_b16 v39, v233 offset:352
	ds_write_b16_d16_hi v39, v233 offset:496
	ds_write_b16 v39, v234 offset:640
	ds_write_b16_d16_hi v39, v234 offset:784
	ds_write_b16 v39, v235 offset:928
	ds_write_b16_d16_hi v39, v235 offset:1072
	s_waitcnt lgkmcnt(0)
	s_barrier
	ds_read_b32 v0, v7 offset:27648
	s_ashr_i32 s15, s14, 31
	s_lshl_b64 s[16:17], s[14:15], 14
	s_add_u32 s16, s46, s16
	s_addc_u32 s17, s47, s17
	s_waitcnt vmcnt(0)
	v_mov_b32_e32 v38, v236
	v_mov_b32_e32 v39, v237
	v_mov_b32_e32 v40, v238
	v_mov_b32_e32 v41, v239
	v_lshlrev_b32_e32 v4, 16, v38
	s_waitcnt lgkmcnt(0)
	v_mul_f32_e32 v4, v0, v4
	v_and_b32_e32 v5, 0xffff0000, v38
	v_cvt_pk_bf16_f32 v4, v4, v1
	v_lshlrev_b32_e32 v37, 16, v39
	v_mul_f32_e32 v5, v0, v5
	ds_write_b16 v23, v4 offset:18432
	v_cvt_pk_bf16_f32 v4, v5, v1
	v_and_b32_e32 v38, 0xffff0000, v39
	v_mul_f32_e32 v37, v0, v37
	ds_write_b16 v23, v4 offset:18576
	v_cvt_pk_bf16_f32 v4, v37, v1
	v_lshlrev_b32_e32 v39, 16, v40
	v_mul_f32_e32 v38, v0, v38
	ds_write_b16 v23, v4 offset:18720
	v_cvt_pk_bf16_f32 v4, v38, v1
	v_and_b32_e32 v40, 0xffff0000, v40
	v_lshlrev_b32_e32 v42, 16, v41
	v_and_b32_e32 v41, 0xffff0000, v41
	v_mul_f32_e32 v39, v0, v39
	ds_write_b16 v23, v4 offset:18864
	v_cvt_pk_bf16_f32 v4, v39, v1
	v_mul_f32_e32 v40, v0, v40
	v_mul_f32_e32 v42, v0, v42
	v_mul_f32_e32 v0, v0, v41
	ds_write_b16 v23, v4 offset:19008
	v_cvt_pk_bf16_f32 v4, v40, v1
	ds_write_b16 v23, v4 offset:19152
	v_cvt_pk_bf16_f32 v4, v42, v1
	ds_write_b16 v23, v4 offset:19296
	v_cvt_pk_bf16_f32 v0, v0, v1
	ds_write_b16 v23, v0 offset:19440
	s_waitcnt lgkmcnt(0)
	s_barrier
	ds_read_b128 v[38:41], v9
	ds_read_b128 v[42:45], v8 offset:18432
	ds_read_b128 v[46:49], v9 offset:64
	ds_read_b128 v[50:53], v8 offset:18496
	ds_read_b128 v[54:57], v8 offset:20736
	ds_read_b128 v[58:61], v8 offset:20800
	ds_read_b128 v[62:65], v8 offset:23040
	ds_read_b128 v[66:69], v8 offset:23104
	ds_read_b128 v[70:73], v8 offset:25344
	ds_read_b128 v[74:77], v8 offset:25408
	s_waitcnt lgkmcnt(8)
	v_mfma_f32_16x16x32_bf16 v[42:45], v[38:41], v[42:45], 0
	s_waitcnt lgkmcnt(5)
	v_mfma_f32_16x16x32_bf16 v[54:57], v[38:41], v[54:57], 0
	s_waitcnt lgkmcnt(3)
	v_mfma_f32_16x16x32_bf16 v[62:65], v[38:41], v[62:65], 0
	s_waitcnt lgkmcnt(1)
	v_mfma_f32_16x16x32_bf16 v[38:41], v[38:41], v[70:73], 0
	v_mfma_f32_16x16x32_bf16 v[42:45], v[46:49], v[50:53], v[42:45]
	v_mfma_f32_16x16x32_bf16 v[50:53], v[46:49], v[58:61], v[54:57]
	v_mfma_f32_16x16x32_bf16 v[54:57], v[46:49], v[66:69], v[62:65]
	s_nop 5
	v_bfe_u32 v0, v42, 16, 1
	v_bfe_u32 v4, v43, 16, 1
	v_bfe_u32 v5, v44, 16, 1
	s_waitcnt lgkmcnt(0)
	v_mfma_f32_16x16x32_bf16 v[38:41], v[46:49], v[74:77], v[38:41]
	v_bfe_u32 v37, v45, 16, 1
	v_bfe_u32 v46, v50, 16, 1
	v_bfe_u32 v47, v51, 16, 1
	v_bfe_u32 v48, v52, 16, 1
	v_bfe_u32 v49, v53, 16, 1
	v_bfe_u32 v58, v54, 16, 1
	v_bfe_u32 v59, v55, 16, 1
	v_bfe_u32 v60, v56, 16, 1
	v_bfe_u32 v61, v57, 16, 1
	v_bfe_u32 v62, v38, 16, 1
	v_bfe_u32 v63, v39, 16, 1
	v_bfe_u32 v64, v40, 16, 1
	v_add3_u32 v0, v42, v0, s43
	v_add3_u32 v4, v43, v4, s43
	v_add3_u32 v5, v44, v5, s43
	v_add3_u32 v37, v45, v37, s43
	v_add3_u32 v42, v50, v46, s43
	v_add3_u32 v43, v51, v47, s43
	v_add3_u32 v44, v52, v48, s43
	v_add3_u32 v45, v53, v49, s43
	v_add3_u32 v46, v54, v58, s43
	v_add3_u32 v47, v55, v59, s43
	v_add3_u32 v48, v56, v60, s43
	v_add3_u32 v49, v57, v61, s43
	v_add3_u32 v38, v38, v62, s43
	v_add3_u32 v39, v39, v63, s43
	global_store_short_d16_hi v24, v0, s[16:17]
	global_store_short_d16_hi v24, v4, s[16:17] offset:128
	global_store_short_d16_hi v24, v5, s[16:17] offset:256
	global_store_short_d16_hi v25, v37, s[16:17]
	global_store_short_d16_hi v24, v42, s[16:17] offset:32
	global_store_short_d16_hi v26, v43, s[16:17] offset:128
	global_store_short_d16_hi v26, v44, s[16:17] offset:256
	global_store_short_d16_hi v25, v45, s[16:17] offset:32
	global_store_short_d16_hi v24, v46, s[16:17] offset:64
	global_store_short_d16_hi v27, v47, s[16:17] offset:128
	global_store_short_d16_hi v27, v48, s[16:17] offset:256
	global_store_short_d16_hi v25, v49, s[16:17] offset:64
	global_store_short_d16_hi v24, v38, s[16:17] offset:96
	global_store_short_d16_hi v28, v39, s[16:17] offset:128
	v_add3_u32 v0, v40, v64, s43
	global_store_short_d16_hi v28, v0, s[16:17] offset:256
	v_bfe_u32 v0, v41, 16, 1
	v_add3_u32 v0, v41, v0, s43
	global_store_short_d16_hi v25, v0, s[16:17] offset:96
	s_and_saveexec_b64 s[16:17], s[4:5]
	s_cbranch_execz .LBB0_655
; __device__ __forceinline__ float bf1(bf16_t u) { return __uint_as_float(((unsigned)u) << 16); }
; __device__ __forceinline__ void phase_mlstm_a(const Args& a, unsigned char* lds) {
;     ...
;         if (tid < 64) { float s = 0.f; for (int k = 0; k < 64; ++k) s += bf1(KT[tid * 72 + k]); DN[item * 64 + tid] = s; }
	ds_read_b128 v[38:41], v10 offset:18432
	ds_read_b128 v[42:45], v10 offset:18448
	ds_read_b128 v[46:49], v10 offset:18464
	ds_read_b128 v[50:53], v10 offset:18480
	s_waitcnt lgkmcnt(3)
	v_lshlrev_b32_e32 v0, 16, v38
	v_and_b32_e32 v4, 0xffff0000, v38
	v_add_f32_e32 v0, 0, v0
	v_add_f32_e32 v0, v0, v4
	v_lshlrev_b32_e32 v4, 16, v39
	v_add_f32_e32 v0, v0, v4
	v_and_b32_e32 v4, 0xffff0000, v39
	v_add_f32_e32 v0, v0, v4
	v_lshlrev_b32_e32 v4, 16, v40
	v_add_f32_e32 v0, v0, v4
	v_and_b32_e32 v4, 0xffff0000, v40
	v_add_f32_e32 v0, v0, v4
	v_lshlrev_b32_e32 v4, 16, v41
	v_add_f32_e32 v0, v0, v4
	v_and_b32_e32 v4, 0xffff0000, v41
	v_add_f32_e32 v0, v0, v4
	s_waitcnt lgkmcnt(2)
	v_lshlrev_b32_e32 v4, 16, v42
	v_add_f32_e32 v0, v0, v4
	v_and_b32_e32 v4, 0xffff0000, v42
	v_add_f32_e32 v0, v0, v4
	v_lshlrev_b32_e32 v4, 16, v43
	v_add_f32_e32 v0, v0, v4
	v_and_b32_e32 v4, 0xffff0000, v43
	v_add_f32_e32 v0, v0, v4
	v_lshlrev_b32_e32 v4, 16, v44
	v_add_f32_e32 v0, v0, v4
	v_and_b32_e32 v4, 0xffff0000, v44
	v_add_f32_e32 v0, v0, v4
	v_lshlrev_b32_e32 v4, 16, v45
	v_add_f32_e32 v0, v0, v4
	v_and_b32_e32 v4, 0xffff0000, v45
	v_add_f32_e32 v0, v0, v4
	s_waitcnt lgkmcnt(1)
	v_lshlrev_b32_e32 v4, 16, v46
	v_add_f32_e32 v0, v0, v4
	v_and_b32_e32 v4, 0xffff0000, v46
	v_add_f32_e32 v0, v0, v4
	v_lshlrev_b32_e32 v4, 16, v47
	v_add_f32_e32 v0, v0, v4
	v_and_b32_e32 v4, 0xffff0000, v47
	v_add_f32_e32 v0, v0, v4
	v_lshlrev_b32_e32 v4, 16, v48
	v_add_f32_e32 v0, v0, v4
	v_and_b32_e32 v4, 0xffff0000, v48
	v_add_f32_e32 v0, v0, v4
	v_lshlrev_b32_e32 v4, 16, v49
	v_add_f32_e32 v0, v0, v4
	v_and_b32_e32 v4, 0xffff0000, v49
	v_add_f32_e32 v0, v0, v4
	s_waitcnt lgkmcnt(0)
	v_lshlrev_b32_e32 v4, 16, v50
	v_add_f32_e32 v0, v0, v4
	v_and_b32_e32 v4, 0xffff0000, v50
	v_add_f32_e32 v0, v0, v4
	v_lshlrev_b32_e32 v4, 16, v51
	v_add_f32_e32 v0, v0, v4
	v_and_b32_e32 v4, 0xffff0000, v51
	ds_read_b128 v[38:41], v10 offset:18496
	ds_read_b128 v[42:45], v10 offset:18512
	v_add_f32_e32 v0, v0, v4
	v_lshlrev_b32_e32 v4, 16, v52
	v_add_f32_e32 v0, v0, v4
	v_and_b32_e32 v4, 0xffff0000, v52
	v_add_f32_e32 v0, v0, v4
	v_lshlrev_b32_e32 v4, 16, v53
	v_add_f32_e32 v0, v0, v4
	v_and_b32_e32 v4, 0xffff0000, v53
	v_add_f32_e32 v0, v0, v4
	s_waitcnt lgkmcnt(1)
	v_lshlrev_b32_e32 v4, 16, v38
	v_add_f32_e32 v0, v0, v4
	v_and_b32_e32 v4, 0xffff0000, v38
	v_add_f32_e32 v0, v0, v4
	v_lshlrev_b32_e32 v4, 16, v39
	v_add_f32_e32 v0, v0, v4
	v_and_b32_e32 v4, 0xffff0000, v39
	v_add_f32_e32 v0, v0, v4
	v_lshlrev_b32_e32 v4, 16, v40
	v_add_f32_e32 v0, v0, v4
	v_and_b32_e32 v4, 0xffff0000, v40
	v_add_f32_e32 v0, v0, v4
	v_lshlrev_b32_e32 v4, 16, v41
	v_add_f32_e32 v0, v0, v4
	v_and_b32_e32 v4, 0xffff0000, v41
	v_add_f32_e32 v0, v0, v4
	s_waitcnt lgkmcnt(0)
	v_lshlrev_b32_e32 v4, 16, v42
	v_add_f32_e32 v0, v0, v4
	v_and_b32_e32 v4, 0xffff0000, v42
	v_add_f32_e32 v0, v0, v4
	v_lshlrev_b32_e32 v4, 16, v43
	v_add_f32_e32 v0, v0, v4
	v_and_b32_e32 v4, 0xffff0000, v43
	ds_read_b128 v[38:41], v10 offset:18528
	v_add_f32_e32 v0, v0, v4
	v_lshlrev_b32_e32 v4, 16, v44
	v_add_f32_e32 v0, v0, v4
	v_and_b32_e32 v4, 0xffff0000, v44
	v_add_f32_e32 v0, v0, v4
	v_lshlrev_b32_e32 v4, 16, v45
	v_add_f32_e32 v0, v0, v4
	v_and_b32_e32 v4, 0xffff0000, v45
	v_add_f32_e32 v0, v0, v4
	ds_read_b128 v[42:45], v10 offset:18544
	s_waitcnt lgkmcnt(1)
	v_lshlrev_b32_e32 v4, 16, v38
	v_add_f32_e32 v0, v0, v4
	v_and_b32_e32 v4, 0xffff0000, v38
	v_add_f32_e32 v0, v0, v4
	v_lshlrev_b32_e32 v4, 16, v39
	v_add_f32_e32 v0, v0, v4
	v_and_b32_e32 v4, 0xffff0000, v39
	v_add_f32_e32 v0, v0, v4
	v_lshlrev_b32_e32 v4, 16, v40
	v_add_f32_e32 v0, v0, v4
	v_and_b32_e32 v4, 0xffff0000, v40
	v_add_f32_e32 v0, v0, v4
	v_lshlrev_b32_e32 v4, 16, v41
	v_add_f32_e32 v0, v0, v4
	v_and_b32_e32 v4, 0xffff0000, v41
	v_add_f32_e32 v0, v0, v4
	s_waitcnt lgkmcnt(0)
	v_lshlrev_b32_e32 v4, 16, v42
	v_add_f32_e32 v0, v0, v4
	v_and_b32_e32 v4, 0xffff0000, v42
	v_add_f32_e32 v0, v0, v4
	v_lshlrev_b32_e32 v4, 16, v43
	v_add_f32_e32 v0, v0, v4
	v_and_b32_e32 v4, 0xffff0000, v43
	v_add_f32_e32 v0, v0, v4
	v_lshlrev_b32_e32 v4, 16, v44
	v_add_f32_e32 v0, v0, v4
	v_and_b32_e32 v4, 0xffff0000, v44
	v_add_f32_e32 v0, v0, v4
	v_lshlrev_b32_e32 v4, 16, v45
	v_add_f32_e32 v0, v0, v4
	v_and_b32_e32 v4, 0xffff0000, v45
	v_add_f32_e32 v0, v0, v4
	v_or_b32_e32 v4, s60, v156
	v_ashrrev_i32_e32 v5, 31, v4
	v_lshl_add_u64 v[4:5], v[4:5], 2, s[36:37]
	global_store_dword v[4:5], v0, off
	s_branch .LBB0_655

; __device__ __forceinline__ float logsigmoidf_(float x) { return fminf(x, 0.f) - log1pf(__expf(-fabsf(x))); }
; __device__ __forceinline__ void phase_mlstm_c(const Args& a, unsigned char* lds) {
;     ...
;         const int c = item & 127, h = (item >> 7) & 3, b = item >> 9;
;         const size_t r0 = (size_t)b * SEQ + c * 64;
;         if (wave == 0) {
;             const float ig = SM[(r0 + lane) * 16 + 8 + h] + a.in[I_BI][h];
;             const float lf = logsigmoidf_(SM[(r0 + lane) * 16 + 12 + h] + a.in[I_BF][h]);
;             const float bs = wave_incl_sum(lf, lane);
;             const float av = ig - bs;
;             const float pm = wave_incl_max(av, lane);
;             const float m0 = MS[item];
;             const float mt = bs + fmaxf(pm, m0);
;             bS[lane] = bs; aS[lane] = av; mtS[lane] = mt; wiS[lane] = __expf(bs + m0 - mt);
;             nS[lane] = DN[item * 64 + lane];
.LBB0_795:
	s_ashr_i32 s64, s62, 9
	s_ashr_i32 s65, s64, 31
	s_lshl_b32 s92, s62, 6
	s_lshl_b64 s[64:65], s[64:65], 13
	s_and_b32 s33, s92, 0x1fc0
	s_ashr_i32 s63, s62, 31
	s_bfe_u32 s91, s62, 0x20007
	s_or_b32 s66, s64, s33
	s_mov_b32 s67, s65
	v_lshl_add_u64 v[252:253], s[66:67], 0, v[128:129]
	v_mov_b64_e32 v[248:249], s[44:45]
	v_mov_b32_e32 v251, v5
	v_mad_u64_u32 v[248:249], vcc, v252, s88, v[248:249]
	s_lshl_b32 s38, s91, 8
	v_mov_b32_e32 v250, v249
	v_mad_u64_u32 v[250:251], vcc, v253, s88, v[250:251]
	s_nop 0
	v_mov_b32_e32 v249, v250
	v_lshl_add_u64 v[248:249], v[248:249], 0, s[38:39]
	v_lshlrev_b32_e32 v250, 1, v6
	v_mov_b32_e32 v251, v5
	v_lshl_add_u64 v[250:251], v[248:249], 0, v[250:251]
	v_add_co_u32_e32 v248, vcc, s89, v250
	s_nop 1
	v_addc_co_u32_e32 v249, vcc, 0, v251, vcc
	global_load_dwordx4 v[220:223], v[248:249], off offset:640
	v_lshl_add_u64 v[252:253], v[250:251], 0, s[60:61]
	global_load_dwordx4 v[224:227], v[252:253], off offset:16
	s_nop 0
	v_lshl_add_u64 v[252:253], s[66:67], 0, v[128:129]
	v_lshlrev_b64 v[252:253], 10, v[252:253]
	v_lshl_add_u64 v[252:253], s[0:1], 0, v[252:253]
	s_lshl_b32 s38, s91, 7
	v_lshl_add_u64 v[252:253], v[252:253], 0, s[38:39]
	v_mov_b32_e32 v251, v5
	v_mov_b32_e32 v250, v12
	v_lshl_add_u64 v[252:253], v[252:253], 0, v[250:251]
	global_load_dwordx4 v[228:231], v[252:253], off
	global_load_dwordx4 v[232:235], v[252:253], off offset:512
	s_lshr_b32 s33, s62, 7
	s_and_b32 s38, s81, 0x1fc0
	s_and_b32 s33, s33, 3
	s_add_u32 s64, s38, s64
	s_addc_u32 s65, 0, s65
	v_lshl_add_u64 v[252:253], s[64:65], 0, v[16:17]
	v_mad_u64_u32 v[250:251], vcc, v252, s88, 0
	v_mad_i32_i24 v253, v253, s88, v251
	v_lshl_or_b32 v252, s33, 8, v250
	v_lshl_add_u64 v[252:253], v[8:9], 0, v[252:253]
	s_lshl_b64 s[94:95], s[62:63], 14
	global_load_dwordx4 v[236:239], v[252:253], off
	s_nop 0
	v_lshl_add_u64 v[252:253], v[252:253], 0, s[40:41]
	global_load_dwordx4 v[240:243], v[252:253], off
	s_nop 0
	v_lshl_add_u64 v[252:253], v[10:11], 0, s[94:95]
	global_load_dwordx4 v[244:247], v[252:253], off
	s_nop 0
	v_lshl_add_u64 v[252:253], v[252:253], 0, s[42:43]
	global_load_dwordx4 v[248:251], v[252:253], off
	s_and_saveexec_b64 s[76:77], s[4:5]
	s_cbranch_execz .LBB0_797
	s_setprio 3
	v_mov_b32_e32 v1, s67
	v_or_b32_e32 v0, s66, v156
	v_lshlrev_b64 v[0:1], 6, v[0:1]
	v_lshl_add_u64 v[0:1], s[58:59], 0, v[0:1]
	s_lshl_b32 s38, s91, 2
	v_lshl_add_u64 v[0:1], v[0:1], 0, s[38:39]
	v_mov_b32_e32 v2, s38
	global_load_dword v3, v[0:1], off offset:48
	global_load_dword v4, v2, s[50:51]
	s_nop 0
	global_load_dword v2, v2, s[48:49]
	s_nop 0
	global_load_dword v13, v[0:1], off offset:32
	s_lshl_b64 s[94:95], s[62:63], 2
	v_or_b32_e32 v0, s92, v156
	s_add_u32 s92, s78, s94
	v_ashrrev_i32_e32 v1, 31, v0
	s_addc_u32 s93, s79, s95
	v_lshl_add_u64 v[0:1], v[0:1], 2, s[36:37]
	global_load_dword v77, v5, s[92:93]
	global_load_dword v78, v[0:1], off
	v_mov_b32_e32 v14, v5
	v_mov_b32_e32 v15, v5
	v_mov_b32_e32 v71, 0xff800000
	v_mov_b32_e32 v72, 0xff800000
	v_mov_b32_e32 v73, 0xff800000
	v_mov_b32_e32 v74, 0xff800000
	v_mov_b32_e32 v75, 0xff800000
	v_mov_b32_e32 v76, 0xff800000
	s_waitcnt vmcnt(4)
	v_add_f32_e32 v3, v3, v4
	v_mul_f32_e64 v4, |v3|, s83
	v_exp_f32_e32 v4, v4
	s_waitcnt vmcnt(2)
; __device__ __forceinline__ bf16_t f2bf(float f) { return (bf16_t)(cvt_pk_bf16(f, 0.f) & 0xffffu); }
; __device__ __forceinline__ float logsigmoidf_(float x) { return fminf(x, 0.f) - log1pf(__expf(-fabsf(x))); }
; __device__ __forceinline__ void phase_mlstm_c(const Args& a, unsigned char* lds) {
;     ...
;         if (wave == 0) {
;             const float ig = SM[(r0 + lane) * 16 + 8 + h] + a.in[I_BI][h];
;             const float lf = logsigmoidf_(SM[(r0 + lane) * 16 + 12 + h] + a.in[I_BF][h]);
;             const float bs = wave_incl_sum(lf, lane);
;             const float av = ig - bs;
;             const float pm = wave_incl_max(av, lane);
;             const float m0 = MS[item];
;             const float mt = bs + fmaxf(pm, m0);
;             bS[lane] = bs; aS[lane] = av; mtS[lane] = mt; wiS[lane] = __expf(bs + m0 - mt);
;             nS[lane] = DN[item * 64 + lane];
;         }
;         { const int s = tid >> 3, d0 = (tid & 7) * 8;
;             *(u32x4*)(QS_ + s * 72 + d0) = *(const u32x4*)(QK + (r0 + s) * 512 + h * 64 + d0);
;             *(u32x4*)(KS + s * 72 + d0) = *(const u32x4*)(QK + (r0 + s) * 512 + 256 + h * 64 + d0); }
;         for (int i = tid; i < 1024; i += 512) { const int s = i >> 4, d0 = (i & 15) * 8; float f[8]; unpack8(*(const u32x4*)(P + (r0 + s) * LDP + C_MV + h * 128 + d0), f);
; #pragma unroll
;             for (int e = 0; e < 8; ++e) BT[(d0 + e) * 136 + s] = f2bf(f[e]); }
;         { const bf16_t* st = ST + (size_t)item * 8192;
;             for (int i = tid; i < 1024; i += 512) { const int dv = i >> 3, k0 = (i & 7) * 8; *(u32x4*)(BT + dv * 136 + 64 + k0) = *(const u32x4*)(st + dv * 64 + k0); } }
;         __syncthreads();
; #pragma unroll
;         for (int u = 0; u < 2; ++u) {
;             const int id = wave * 2 + u, tr = id >> 2, tc = id & 3;
;             f32x4 acc = (f32x4){0.f, 0.f, 0.f, 0.f};
;             if (tc <= tr) acc = mma_lds(QS_ + tr * 16 * 72, 72, KS + tc * 16 * 72, 72, 64, lane);
	v_add_f32_e32 v2, v13, v2
	v_min_f32_e32 v3, 0, v3
	v_add_f32_e32 v13, 1.0, v4
	v_add_f32_e32 v79, -1.0, v13
	v_frexp_mant_f32_e32 v80, v13
	v_cvt_f64_f32_e32 v[0:1], v13
	v_sub_f32_e32 v81, v79, v13
	v_frexp_exp_i32_f64_e32 v0, v[0:1]
	v_cmp_gt_f32_e32 vcc, s84, v80
	v_sub_f32_e32 v79, v4, v79
	v_add_f32_e32 v1, 1.0, v81
	v_subbrev_co_u32_e32 v0, vcc, 0, v0, vcc
	v_add_f32_e32 v1, v79, v1
	v_sub_u32_e32 v79, 0, v0
	v_cvt_f32_i32_e32 v0, v0
	v_ldexp_f32 v13, v13, v79
	v_ldexp_f32 v1, v1, v79
	v_add_f32_e32 v79, -1.0, v13
	v_add_f32_e32 v80, 1.0, v13
	v_add_f32_e32 v81, 1.0, v79
	v_add_f32_e32 v82, -1.0, v80
	v_sub_f32_e32 v81, v13, v81
	v_sub_f32_e32 v13, v13, v82
	v_mul_f32_e32 v82, 0x3f317218, v0
	v_add_f32_e32 v81, v1, v81
	v_add_f32_e32 v1, v1, v13
	v_fma_f32 v13, v0, s85, -v82
	v_add_f32_e32 v83, v79, v81
	v_add_f32_e32 v84, v80, v1
	v_fmac_f32_e32 v13, 0xb102e308, v0
	v_sub_f32_e32 v0, v83, v79
	v_sub_f32_e32 v79, v84, v80
	v_rcp_f32_e32 v80, v84
	v_add_f32_e32 v85, v82, v13
	v_sub_f32_e32 v1, v1, v79
	v_sub_f32_e32 v79, v85, v82
	v_sub_f32_e32 v13, v13, v79
	v_mul_f32_e32 v79, v83, v80
	v_sub_f32_e32 v0, v81, v0
	v_mul_f32_e32 v81, v84, v79
	v_fma_f32 v82, v79, v84, -v81
	v_fmac_f32_e32 v82, v79, v1
	v_add_f32_e32 v86, v81, v82
	v_sub_f32_e32 v87, v83, v86
	v_sub_f32_e32 v81, v86, v81
	v_sub_f32_e32 v83, v83, v87
	v_sub_f32_e32 v81, v81, v82
	v_sub_f32_e32 v82, v83, v86
	v_add_f32_e32 v0, v0, v82
	v_add_f32_e32 v0, v81, v0
	v_add_f32_e32 v81, v87, v0
	v_mul_f32_e32 v82, v80, v81
	v_sub_f32_e32 v83, v87, v81
	v_mul_f32_e32 v86, v84, v82
	v_add_f32_e32 v0, v0, v83
	v_add_f32_e32 v83, v79, v82
	v_fma_f32 v84, v82, v84, -v86
	v_sub_f32_e32 v79, v83, v79
	v_fmac_f32_e32 v84, v82, v1
	v_sub_f32_e32 v1, v82, v79
	v_add_f32_e32 v79, v86, v84
	v_sub_f32_e32 v82, v79, v86
	v_sub_f32_e32 v86, v81, v79
	v_sub_f32_e32 v81, v81, v86
	v_sub_f32_e32 v79, v81, v79
	v_sub_f32_e32 v82, v82, v84
	v_add_f32_e32 v0, v0, v79
	v_add_f32_e32 v0, v82, v0
	v_add_f32_e32 v0, v86, v0
	v_mul_f32_e32 v0, v80, v0
	v_add_f32_e32 v0, v1, v0
	v_add_f32_e32 v1, v83, v0
	v_mul_f32_e32 v79, v1, v1
	v_fmamk_f32 v82, v79, 0x3e9b6dac, v61
	v_sub_f32_e32 v80, v1, v83
	v_ldexp_f32 v81, v1, 1
	v_mul_f32_e32 v1, v1, v79
	v_fmaak_f32 v79, v79, v82, 0x3f2aaada
	v_mul_f32_e32 v1, v1, v79
	v_add_f32_e32 v79, v81, v1
	v_sub_f32_e32 v0, v0, v80
	v_sub_f32_e32 v80, v79, v81
	v_ldexp_f32 v0, v0, 1
	v_sub_f32_e32 v1, v1, v80
	v_add_f32_e32 v0, v0, v1
	v_add_f32_e32 v1, v79, v0
	v_sub_f32_e32 v79, v1, v79
	v_add_f32_e32 v80, v85, v1
	v_sub_f32_e32 v0, v0, v79
	v_sub_f32_e32 v79, v80, v85
	v_sub_f32_e32 v81, v80, v79
	v_sub_f32_e32 v1, v1, v79
	v_add_f32_e32 v79, v13, v0
	v_sub_f32_e32 v81, v85, v81
	v_sub_f32_e32 v82, v79, v13
	v_add_f32_e32 v1, v1, v81
	v_sub_f32_e32 v81, v79, v82
	v_sub_f32_e32 v0, v0, v82
	v_sub_f32_e32 v13, v13, v81
	v_add_f32_e32 v1, v79, v1
	v_add_f32_e32 v0, v0, v13
	v_add_f32_e32 v13, v80, v1
	v_sub_f32_e32 v79, v13, v80
	v_sub_f32_e32 v1, v1, v79
	v_add_f32_e32 v0, v0, v1
	v_add_f32_e32 v0, v13, v0
	v_cmp_neq_f32_e32 vcc, s86, v4
	s_nop 1
	v_cndmask_b32_e32 v0, v65, v0, vcc
	v_cmp_ngt_f32_e32 vcc, -1.0, v4
	s_nop 1
	v_cndmask_b32_e32 v0, v66, v0, vcc
	v_cmp_neq_f32_e32 vcc, -1.0, v4
	s_nop 1
	v_cndmask_b32_e32 v0, v62, v0, vcc
	v_cmp_lt_f32_e64 vcc, |v4|, s87
	s_nop 1
	v_cndmask_b32_e32 v0, v0, v4, vcc
	v_sub_f32_e32 v0, v3, v0
	s_nop 1
	v_add_f32_dpp v0, v0, v0 row_shr:1 row_mask:0xf bank_mask:0xf bound_ctrl:1
	s_nop 1
	v_add_f32_dpp v0, v0, v0 row_shr:2 row_mask:0xf bank_mask:0xf bound_ctrl:1
	s_nop 1
	v_add_f32_dpp v0, v0, v0 row_shr:4 row_mask:0xf bank_mask:0xf bound_ctrl:1
	s_nop 1
	v_add_f32_dpp v0, v0, v0 row_shr:8 row_mask:0xf bank_mask:0xf bound_ctrl:1
	s_nop 1
	v_mov_b32_dpp v14, v0 row_bcast:15 row_mask:0xa bank_mask:0xf
	v_add_f32_e32 v0, v0, v14
	s_nop 1
	v_mov_b32_dpp v15, v0 row_bcast:31 row_mask:0xc bank_mask:0xf
	v_add_f32_e32 v0, v0, v15
	v_sub_f32_e32 v1, v2, v0
	s_waitcnt vmcnt(1)
	v_add_f32_e32 v2, v77, v0
	v_mov_b32_dpp v71, v1 row_shr:1 row_mask:0xf bank_mask:0xf
	v_max_f32_e32 v3, v71, v71
	v_max_f32_e32 v3, v1, v3
	s_nop 1
	v_mov_b32_dpp v72, v3 row_shr:2 row_mask:0xf bank_mask:0xf
	v_max_f32_e32 v4, v72, v72
	v_max_f32_e32 v3, v3, v4
	s_nop 1
	v_mov_b32_dpp v73, v3 row_shr:4 row_mask:0xf bank_mask:0xf
	v_max_f32_e32 v4, v73, v73
	v_max_f32_e32 v3, v3, v4
	s_nop 1
	v_mov_b32_dpp v74, v3 row_shr:8 row_mask:0xf bank_mask:0xf
	v_max_f32_e32 v4, v74, v74
	v_max_f32_e32 v3, v3, v4
	s_nop 1
	v_mov_b32_dpp v75, v3 row_bcast:15 row_mask:0xa bank_mask:0xf
	v_max_f32_e32 v4, v75, v75
	v_max_f32_e32 v3, v3, v4
	s_nop 1
	v_mov_b32_dpp v76, v3 row_bcast:31 row_mask:0xc bank_mask:0xf
	v_max3_f32 v3, v3, v76, v77
	v_add_f32_e32 v3, v0, v3
	v_sub_f32_e32 v2, v2, v3
	v_mul_f32_e32 v2, 0x3fb8aa3b, v2
	v_exp_f32_e32 v2, v2
	ds_write_b32 v7, v0
	ds_write_b32 v18, v1
	ds_write_b32 v19, v3
	ds_write_b32 v20, v2
	s_waitcnt vmcnt(0)
	ds_write_b32 v21, v78
.LBB0_797:
	s_or_b64 exec, exec, s[76:77]
	s_setprio 0
	v_lshl_add_u64 v[14:15], s[66:67], 0, v[128:129]
	v_and_b32_e32 v13, 0x78, v162
	v_mad_u32_u24 v13, v13, s80, v60
	s_waitcnt vmcnt(5)
	ds_write_b128 v22, v[228:231]
	s_waitcnt vmcnt(4)
	ds_write_b128 v22, v[232:235] offset:9216
	s_waitcnt vmcnt(3)
	ds_write_b16 v13, v236
	ds_write_b16_d16_hi v13, v236 offset:272
	ds_write_b16 v13, v237 offset:544
	ds_write_b16_d16_hi v13, v237 offset:816
	ds_write_b16 v13, v238 offset:1088
	ds_write_b16_d16_hi v13, v238 offset:1360
	ds_write_b16 v13, v239 offset:1632
	ds_write_b16_d16_hi v13, v239 offset:1904
	s_waitcnt vmcnt(2)
	ds_write_b16 v13, v240 offset:64
	ds_write_b16_d16_hi v13, v240 offset:336
	ds_write_b16 v13, v241 offset:608
	ds_write_b16_d16_hi v13, v241 offset:880
	ds_write_b16 v13, v242 offset:1152
	ds_write_b16_d16_hi v13, v242 offset:1424
	ds_write_b16 v13, v243 offset:1696
	ds_write_b16_d16_hi v13, v243 offset:1968
	s_waitcnt vmcnt(1)
	ds_write_b128 v32, v[244:247]
	s_waitcnt vmcnt(0)
	ds_write_b128 v32, v[248:251] offset:17408
	v_mov_b32_e32 v4, 0
	v_mov_b32_e32 v0, 0
	v_mov_b32_e32 v1, 0
	v_mov_b32_e32 v2, 0
	v_mov_b32_e32 v3, 0
	s_waitcnt lgkmcnt(0)
	s_barrier
	s_and_saveexec_b64 s[64:65], s[8:9]
	s_cbranch_execz .LBB0_803
	ds_read_b128 v[0:3], v23
	ds_read_b128 v[72:75], v23 offset:64
	ds_read_b128 v[76:79], v67 offset:9216
	ds_read_b128 v[80:83], v67 offset:9280
	s_waitcnt lgkmcnt(1)
	v_mfma_f32_16x16x32_bf16 v[0:3], v[0:3], v[76:79], 0
	s_waitcnt lgkmcnt(0)
	v_mfma_f32_16x16x32_bf16 v[0:3], v[72:75], v[80:83], v[0:3]
